# HGRN2 scan: prompt-chunk waves run at s_setprio 1 so the sample-stream wave sharing SIMD 0 only uses spare issue slots
# speedup vs baseline: 1.0036x; 1.0024x over previous
; __device__ __forceinline__ int bidx() { int b = blockIdx.x; asm volatile("" : "+s"(b)); return b; }
; __device__ __forceinline__ float lb_of(const Ctx& p, int l, int c) { if (l == 0) return 0.f; const float* z = INP(p, 21); const float z0 = z[c], z1 = z[512 + c]; return __builtin_amdgcn_rcpf(1.0f + __expf(z0 - z1)); }
; __device__ void phase_hgrn_scan(const Ctx& p, int l, LAS unsigned char* lds) {
;     ...
;     for (int item = bidx() * 8 + wave; item < 2048; item += gridDim.x * 8) {
;         const int kh = item & 1, half = (item >> 1) & 1, h = (item >> 2) & 3, c = (item >> 4) & 63, b = item >> 10, idx = item >> 2;
;         f2 S[32];
; #pragma unroll
;         for (int k = 0; k < 32; ++k) S[k] = (f2){0.f, 0.f};
;         float cp = 1.f;
;         hgrn_scan(PH, b * 8192 + c * 128, 128, h, half, kh, lane, lb_of(p, l, h * 128 + kh * 64 + lane), S, cp, kh ? OH1 : OH0, half == 0 ? PGC + (size_t)idx * 384 + kh * 64 : nullptr, L);
.LBB0_462:
	s_andn2_b64 vcc, exec, s[0:1]
	s_cbranch_vccnz .LBB0_486
	v_readfirstlane_b32 s38, v184
	s_lshr_b32 s38, s38, 6
	s_add_u32 s24, s86, 0x5500000
	s_addc_u32 s25, s87, 0
	s_cmp_gt_u32 s38, 4
	s_cbranch_scc1 .LBB0_486
	s_cmp_eq_u32 s38, 4
	s_cbranch_scc1 .Lhs_role_s
	s_lshl_b32 s0, s90, 2
	s_add_i32 s0, s0, s38
	s_cmpk_gt_u32 s0, 0x3ff
	s_cbranch_scc1 .LBB0_486
	s_and_b32 s1, s0, 1
	s_bfe_u32 s2, s0, 0x20001
	s_lshr_b32 s3, s0, 1
	s_lshr_b32 s4, s0, 3
	s_lshl_b32 s4, s4, 7
	s_mov_b32 s36, 32
	s_lshl_b32 s5, s3, 16
	s_lshl_b32 s6, s1, 15
	s_add_i32 s5, s5, s6
	s_add_u32 s40, s86, 0xcc00000
	s_addc_u32 s41, s87, 0
	s_add_u32 s40, s40, s5
	s_addc_u32 s41, s41, 0
	s_mul_i32 s5, s3, 0x600
	s_lshl_b32 s6, s1, 8
	s_add_i32 s5, s5, s6
	s_add_u32 s42, s86, 0xec00000
	s_addc_u32 s43, s87, 0
	s_add_u32 s42, s42, s5
	s_addc_u32 s43, s43, 0
	s_lshl_b32 s5, s3, 9
	s_add_i32 s5, s5, s6
	s_add_u32 s44, s86, 0x2150000
	s_addc_u32 s45, s87, 0
	s_add_u32 s44, s44, s5
	s_addc_u32 s45, s45, 0
	s_setprio 1
	s_branch .Lhs_common

; __device__ void phase_hgrn_scan(const Ctx& p, int l, LAS unsigned char* lds) {
;     ...
;     }
; }
.Lhs_restore:
	s_setprio 0
	v_mov_b64_e32 v[130:131], 0x43f
	v_mov_b64_e32 v[132:133], 0x440
	v_mov_b64_e32 v[134:135], 0xff
	v_mov_b64_e32 v[136:137], 0x100
	v_mov_b64_e32 v[140:141], 0x21f
	v_mov_b64_e32 v[142:143], 0x220
	v_mov_b64_e32 v[144:145], 0x1ff
	v_mov_b64_e32 v[146:147], 0x200
	v_mov_b32_e32 v138, 1.0
	s_branch .LBB0_486
